# MLP1 epilogue: row-group waits vmcnt(0)->vmcnt(2) so they stop waiting for the two stores just issued (stores always execute there)
# speedup vs baseline: 1.0589x; 1.0021x over previous
.LBB0_145:
	s_or_b64 exec, exec, s[0:1]
	s_waitcnt vmcnt(2)
	v_pk_add_f32 v[78:79], v[164:165], v[166:167]
	v_pk_add_f32 v[144:145], v[160:161], v[162:163]
	s_mov_b32 s0, 0x3a800000
	v_pk_add_f32 v[78:79], v[78:79], v[144:145]
	v_lshlrev_b64 v[158:159], 13, v[200:201]
	v_pk_mul_f32 v[154:155], v[78:79], s[0:1] op_sel_hi:[1,0]
	s_mov_b32 s0, 0x800000
	v_fma_f32 v78, -v154, v154, v155
	v_max_f32_e32 v78, 0, v78
	v_add_f32_e32 v78, 0x3727c5ac, v78
	v_cmp_gt_f32_e64 s[0:1], s0, v78
	v_mul_f32_e32 v79, 0x4b800000, v78
	v_lshl_add_u64 v[158:159], s[24:25], 0, v[158:159]
	v_cndmask_b32_e64 v78, v78, v79, s[0:1]
	v_rsq_f32_e32 v78, v78
	v_lshl_add_u64 v[158:159], v[196:197], 1, v[158:159]
	v_mov_b32_e32 v155, v154
	v_mul_f32_e32 v79, 0x45800000, v78
	v_cndmask_b32_e64 v156, v78, v79, s[0:1]
	v_add_u32_e32 v78, 32, v198
	v_ashrrev_i32_e32 v79, 31, v78
	v_lshlrev_b64 v[144:145], 5, v[78:79]
	v_lshl_add_u64 v[148:149], s[56:57], 0, v[144:145]
	global_load_dwordx4 v[144:147], v[148:149], off offset:16
	s_nop 0
	global_load_dwordx4 v[148:151], v[148:149], off
	v_mov_b32_e32 v157, v156
	s_and_saveexec_b64 s[0:1], vcc
	s_cbranch_execz .LBB0_147
	v_pk_fma_f32 v[136:137], v[92:93], v[154:155], v[136:137] neg_lo:[1,0,0] neg_hi:[1,0,0]
	v_mov_b32_e32 v160, v154
	v_pk_fma_f32 v[136:137], v[136:137], v[156:157], v[88:89]
	v_mov_b32_e32 v161, v154
	v_max_f32_e32 v136, 0, v136
	v_max_f32_e32 v137, 0, v137
	v_pk_mul_f32 v[136:137], v[136:137], v[136:137]
	v_pk_fma_f32 v[142:143], v[102:103], v[160:161], v[142:143]
	v_mov_b32_e32 v162, v156
	v_mov_b32_e32 v163, v156
	v_pk_fma_f32 v[138:139], v[94:95], v[160:161], v[138:139]
	v_pk_fma_f32 v[138:139], v[138:139], v[162:163], v[90:91]
	v_max_f32_e32 v138, 0, v138
	v_max_f32_e32 v139, 0, v139
	v_pk_fma_f32 v[140:141], v[100:101], v[154:155], v[140:141] neg_lo:[1,0,0] neg_hi:[1,0,0]
	v_pk_mul_f32 v[138:139], v[138:139], v[138:139]
	v_pk_fma_f32 v[140:141], v[140:141], v[156:157], v[96:97]
	v_cvt_pk_bf16_f32 v136, v136, v137
	v_bfe_u32 v137, v139, 16, 1
	v_max_f32_e32 v140, 0, v140
	v_max_f32_e32 v141, 0, v141
	v_add3_u32 v137, v139, v137, s96
	v_bfe_u32 v139, v138, 16, 1
	v_pk_fma_f32 v[142:143], v[142:143], v[162:163], v[98:99]
	v_pk_mul_f32 v[140:141], v[140:141], v[140:141]
	v_add3_u32 v138, v138, v139, s96
	v_max_f32_e32 v142, 0, v142
	v_max_f32_e32 v143, 0, v143
	v_lshrrev_b32_e32 v138, 16, v138
	v_bfe_u32 v139, v140, 16, 1
	v_pk_mul_f32 v[142:143], v[142:143], v[142:143]
	v_and_or_b32 v137, v137, s97, v138
	v_bfe_u32 v138, v141, 16, 1
	v_add3_u32 v139, v140, v139, s96
	v_add3_u32 v138, v141, v138, s96
	v_lshrrev_b32_e32 v139, 16, v139
	v_and_or_b32 v138, v138, s97, v139
	v_cvt_pk_bf16_f32 v139, v142, v143
	global_store_dwordx4 v[158:159], v[136:139], off

.LBB0_149:
	s_or_b64 exec, exec, s[0:1]
	s_waitcnt vmcnt(2)
	v_pk_add_f32 v[128:129], v[148:149], v[150:151]
	v_pk_add_f32 v[130:131], v[144:145], v[146:147]
	s_mov_b32 s0, 0x3a800000
	v_pk_add_f32 v[128:129], v[128:129], v[130:131]
	v_add_u32_e32 v136, 48, v198
	v_pk_mul_f32 v[138:139], v[128:129], s[0:1] op_sel_hi:[1,0]
	s_mov_b32 s0, 0x800000
	v_fma_f32 v128, -v138, v138, v139
	v_max_f32_e32 v128, 0, v128
	v_add_f32_e32 v128, 0x3727c5ac, v128
	v_cmp_gt_f32_e64 s[0:1], s0, v128
	v_mul_f32_e32 v129, 0x4b800000, v128
	v_ashrrev_i32_e32 v137, 31, v136
	v_cndmask_b32_e64 v128, v128, v129, s[0:1]
	v_rsq_f32_e32 v128, v128
	v_lshlrev_b64 v[78:79], 13, v[78:79]
	v_lshl_add_u64 v[78:79], s[24:25], 0, v[78:79]
	v_mul_f32_e32 v129, 0x45800000, v128
	v_cndmask_b32_e64 v140, v128, v129, s[0:1]
	v_lshlrev_b64 v[128:129], 5, v[136:137]
	v_lshl_add_u64 v[132:133], s[56:57], 0, v[128:129]
	global_load_dwordx4 v[128:131], v[132:133], off offset:16
	s_nop 0
	global_load_dwordx4 v[132:135], v[132:133], off
	v_lshl_add_u64 v[78:79], v[196:197], 1, v[78:79]
	v_mov_b32_e32 v139, v138
	v_mov_b32_e32 v141, v140
	s_and_saveexec_b64 s[0:1], vcc
	s_cbranch_execz .LBB0_151
	v_pk_fma_f32 v[120:121], v[92:93], v[138:139], v[120:121] neg_lo:[1,0,0] neg_hi:[1,0,0]
	v_mov_b32_e32 v142, v138
	v_pk_fma_f32 v[120:121], v[120:121], v[140:141], v[88:89]
	v_mov_b32_e32 v143, v138
	v_max_f32_e32 v120, 0, v120
	v_max_f32_e32 v121, 0, v121
	v_pk_mul_f32 v[120:121], v[120:121], v[120:121]
	v_pk_fma_f32 v[126:127], v[102:103], v[142:143], v[126:127]
	v_mov_b32_e32 v144, v140
	v_mov_b32_e32 v145, v140
	v_pk_fma_f32 v[122:123], v[94:95], v[142:143], v[122:123]
	v_pk_fma_f32 v[122:123], v[122:123], v[144:145], v[90:91]
	v_max_f32_e32 v122, 0, v122
	v_max_f32_e32 v123, 0, v123
	v_pk_fma_f32 v[124:125], v[100:101], v[138:139], v[124:125] neg_lo:[1,0,0] neg_hi:[1,0,0]
	v_pk_mul_f32 v[122:123], v[122:123], v[122:123]
	v_pk_fma_f32 v[124:125], v[124:125], v[140:141], v[96:97]
	v_cvt_pk_bf16_f32 v120, v120, v121
	v_bfe_u32 v121, v123, 16, 1
	v_max_f32_e32 v124, 0, v124
	v_max_f32_e32 v125, 0, v125
	v_add3_u32 v121, v123, v121, s96
	v_bfe_u32 v123, v122, 16, 1
	v_pk_fma_f32 v[126:127], v[126:127], v[144:145], v[98:99]
	v_pk_mul_f32 v[124:125], v[124:125], v[124:125]
	v_add3_u32 v122, v122, v123, s96
	v_max_f32_e32 v126, 0, v126
	v_max_f32_e32 v127, 0, v127
	v_lshrrev_b32_e32 v122, 16, v122
	v_bfe_u32 v123, v124, 16, 1
	v_pk_mul_f32 v[126:127], v[126:127], v[126:127]
	v_and_or_b32 v121, v121, s97, v122
	v_bfe_u32 v122, v125, 16, 1
	v_add3_u32 v123, v124, v123, s96
	v_add3_u32 v122, v125, v122, s96
	v_lshrrev_b32_e32 v123, 16, v123
	v_and_or_b32 v122, v122, s97, v123
	v_cvt_pk_bf16_f32 v123, v126, v127
	global_store_dwordx4 v[78:79], v[120:123], off

.LBB0_153:
	s_or_b64 exec, exec, s[0:1]
	s_waitcnt vmcnt(2)
	v_pk_add_f32 v[78:79], v[132:133], v[134:135]
	v_pk_add_f32 v[112:113], v[128:129], v[130:131]
	s_mov_b32 s0, 0x3a800000
	v_pk_add_f32 v[78:79], v[78:79], v[112:113]
	v_add_u32_e32 v120, 0x80, v198
	v_pk_mul_f32 v[78:79], v[78:79], s[0:1] op_sel_hi:[1,0]
	s_mov_b32 s0, 0x800000
	v_fma_f32 v79, -v78, v78, v79
	v_max_f32_e32 v79, 0, v79
	v_add_f32_e32 v79, 0x3727c5ac, v79
	v_cmp_gt_f32_e64 s[0:1], s0, v79
	v_mul_f32_e32 v112, 0x4b800000, v79
	v_ashrrev_i32_e32 v121, 31, v120
	v_cndmask_b32_e64 v79, v79, v112, s[0:1]
	v_rsq_f32_e32 v79, v79
	v_lshlrev_b64 v[124:125], 13, v[136:137]
	v_lshl_add_u64 v[124:125], s[24:25], 0, v[124:125]
	v_mul_f32_e32 v112, 0x45800000, v79
	v_cndmask_b32_e64 v122, v79, v112, s[0:1]
	v_lshlrev_b64 v[112:113], 5, v[120:121]
	v_lshl_add_u64 v[116:117], s[56:57], 0, v[112:113]
	global_load_dwordx4 v[112:115], v[116:117], off offset:16
	s_nop 0
	global_load_dwordx4 v[116:119], v[116:117], off
	v_lshl_add_u64 v[124:125], v[196:197], 1, v[124:125]
	v_mov_b32_e32 v79, v78
	v_mov_b32_e32 v123, v122
	s_and_saveexec_b64 s[0:1], vcc
	s_cbranch_execz .LBB0_155
	v_pk_fma_f32 v[104:105], v[92:93], v[78:79], v[104:105] neg_lo:[1,0,0] neg_hi:[1,0,0]
	v_mov_b32_e32 v126, v78
	v_pk_fma_f32 v[104:105], v[104:105], v[122:123], v[88:89]
	v_mov_b32_e32 v127, v78
	v_max_f32_e32 v104, 0, v104
	v_max_f32_e32 v105, 0, v105
	v_pk_mul_f32 v[104:105], v[104:105], v[104:105]
	v_pk_fma_f32 v[110:111], v[102:103], v[126:127], v[110:111]
	v_mov_b32_e32 v128, v122
	v_mov_b32_e32 v129, v122
	v_pk_fma_f32 v[106:107], v[94:95], v[126:127], v[106:107]
	v_pk_fma_f32 v[106:107], v[106:107], v[128:129], v[90:91]
	v_max_f32_e32 v106, 0, v106
	v_max_f32_e32 v107, 0, v107
	v_pk_fma_f32 v[108:109], v[100:101], v[78:79], v[108:109] neg_lo:[1,0,0] neg_hi:[1,0,0]
	v_pk_mul_f32 v[106:107], v[106:107], v[106:107]
	v_pk_fma_f32 v[108:109], v[108:109], v[122:123], v[96:97]
	v_cvt_pk_bf16_f32 v104, v104, v105
	v_bfe_u32 v105, v107, 16, 1
	v_max_f32_e32 v108, 0, v108
	v_max_f32_e32 v109, 0, v109
	v_add3_u32 v105, v107, v105, s96
	v_bfe_u32 v107, v106, 16, 1
	v_pk_fma_f32 v[110:111], v[110:111], v[128:129], v[98:99]
	v_pk_mul_f32 v[108:109], v[108:109], v[108:109]
	v_add3_u32 v106, v106, v107, s96
	v_max_f32_e32 v110, 0, v110
	v_max_f32_e32 v111, 0, v111
	v_lshrrev_b32_e32 v106, 16, v106
	v_bfe_u32 v107, v108, 16, 1
	v_pk_mul_f32 v[110:111], v[110:111], v[110:111]
	v_and_or_b32 v105, v105, s97, v106
	v_bfe_u32 v106, v109, 16, 1
	v_add3_u32 v107, v108, v107, s96
	v_add3_u32 v106, v109, v106, s96
	v_lshrrev_b32_e32 v107, 16, v107
	v_and_or_b32 v106, v106, s97, v107
	v_cvt_pk_bf16_f32 v107, v110, v111
	global_store_dwordx4 v[124:125], v[104:107], off

.LBB0_157:
	s_or_b64 exec, exec, s[0:1]
	s_waitcnt vmcnt(2)
	v_pk_add_f32 v[78:79], v[116:117], v[118:119]
	v_pk_add_f32 v[80:81], v[112:113], v[114:115]
	s_mov_b32 s0, 0x3a800000
	v_pk_add_f32 v[78:79], v[78:79], v[80:81]
	v_add_u32_e32 v86, 0x90, v198
	v_pk_mul_f32 v[104:105], v[78:79], s[0:1] op_sel_hi:[1,0]
	s_mov_b32 s0, 0x800000
	v_fma_f32 v78, -v104, v104, v105
	v_max_f32_e32 v78, 0, v78
	v_add_f32_e32 v78, 0x3727c5ac, v78
	v_cmp_gt_f32_e64 s[0:1], s0, v78
	v_mul_f32_e32 v79, 0x4b800000, v78
	v_ashrrev_i32_e32 v87, 31, v86
	v_cndmask_b32_e64 v78, v78, v79, s[0:1]
	v_rsq_f32_e32 v78, v78
	v_lshlrev_b64 v[108:109], 13, v[120:121]
	v_lshl_add_u64 v[108:109], s[24:25], 0, v[108:109]
	v_mul_f32_e32 v79, 0x45800000, v78
	v_cndmask_b32_e64 v106, v78, v79, s[0:1]
	v_lshlrev_b64 v[78:79], 5, v[86:87]
	v_lshl_add_u64 v[82:83], s[56:57], 0, v[78:79]
	global_load_dwordx4 v[78:81], v[82:83], off offset:16
	s_nop 0
	global_load_dwordx4 v[82:85], v[82:83], off
	v_lshl_add_u64 v[108:109], v[196:197], 1, v[108:109]
	v_mov_b32_e32 v105, v104
	v_mov_b32_e32 v107, v106
	s_and_saveexec_b64 s[0:1], vcc
	s_cbranch_execz .LBB0_159
	v_pk_fma_f32 v[56:57], v[92:93], v[104:105], v[56:57] neg_lo:[1,0,0] neg_hi:[1,0,0]
	v_mov_b32_e32 v110, v104
	v_pk_fma_f32 v[56:57], v[56:57], v[106:107], v[88:89]
	v_mov_b32_e32 v111, v104
	v_max_f32_e32 v56, 0, v56
	v_max_f32_e32 v57, 0, v57
	v_pk_mul_f32 v[56:57], v[56:57], v[56:57]
	v_pk_fma_f32 v[62:63], v[102:103], v[110:111], v[62:63]
	v_mov_b32_e32 v112, v106
	v_mov_b32_e32 v113, v106
	v_pk_fma_f32 v[58:59], v[94:95], v[110:111], v[58:59]
	v_pk_fma_f32 v[58:59], v[58:59], v[112:113], v[90:91]
	v_max_f32_e32 v58, 0, v58
	v_max_f32_e32 v59, 0, v59
	v_pk_fma_f32 v[60:61], v[100:101], v[104:105], v[60:61] neg_lo:[1,0,0] neg_hi:[1,0,0]
	v_pk_mul_f32 v[58:59], v[58:59], v[58:59]
	v_pk_fma_f32 v[60:61], v[60:61], v[106:107], v[96:97]
	v_cvt_pk_bf16_f32 v56, v56, v57
	v_bfe_u32 v57, v59, 16, 1
	v_max_f32_e32 v60, 0, v60
	v_max_f32_e32 v61, 0, v61
	v_add3_u32 v57, v59, v57, s96
	v_bfe_u32 v59, v58, 16, 1
	v_pk_fma_f32 v[62:63], v[62:63], v[112:113], v[98:99]
	v_pk_mul_f32 v[60:61], v[60:61], v[60:61]
	v_add3_u32 v58, v58, v59, s96
	v_max_f32_e32 v62, 0, v62
	v_max_f32_e32 v63, 0, v63
	v_lshrrev_b32_e32 v58, 16, v58
	v_bfe_u32 v59, v60, 16, 1
	v_pk_mul_f32 v[62:63], v[62:63], v[62:63]
	v_and_or_b32 v57, v57, s97, v58
	v_bfe_u32 v58, v61, 16, 1
	v_add3_u32 v59, v60, v59, s96
	v_add3_u32 v58, v61, v58, s96
	v_lshrrev_b32_e32 v59, 16, v59
	v_and_or_b32 v58, v58, s97, v59
	v_cvt_pk_bf16_f32 v59, v62, v63
	global_store_dwordx4 v[108:109], v[56:59], off

.LBB0_161:
	s_or_b64 exec, exec, s[0:1]
	s_waitcnt vmcnt(2)
	v_pk_add_f32 v[48:49], v[82:83], v[84:85]
	v_pk_add_f32 v[50:51], v[78:79], v[80:81]
	s_mov_b32 s0, 0x3a800000
	v_pk_add_f32 v[48:49], v[48:49], v[50:51]
	v_add_u32_e32 v56, 0xa0, v198
	v_pk_mul_f32 v[58:59], v[48:49], s[0:1] op_sel_hi:[1,0]
	s_mov_b32 s0, 0x800000
	v_fma_f32 v48, -v58, v58, v59
	v_max_f32_e32 v48, 0, v48
	v_add_f32_e32 v48, 0x3727c5ac, v48
	v_cmp_gt_f32_e64 s[0:1], s0, v48
	v_mul_f32_e32 v49, 0x4b800000, v48
	v_ashrrev_i32_e32 v57, 31, v56
	v_cndmask_b32_e64 v48, v48, v49, s[0:1]
	v_rsq_f32_e32 v48, v48
	v_lshlrev_b64 v[62:63], 13, v[86:87]
	v_lshl_add_u64 v[62:63], s[24:25], 0, v[62:63]
	v_mul_f32_e32 v49, 0x45800000, v48
	v_cndmask_b32_e64 v60, v48, v49, s[0:1]
	v_lshlrev_b64 v[48:49], 5, v[56:57]
	v_lshl_add_u64 v[52:53], s[56:57], 0, v[48:49]
	global_load_dwordx4 v[48:51], v[52:53], off offset:16
	s_nop 0
	global_load_dwordx4 v[52:55], v[52:53], off
	v_lshl_add_u64 v[62:63], v[196:197], 1, v[62:63]
	v_mov_b32_e32 v59, v58
	v_mov_b32_e32 v61, v60
	s_and_saveexec_b64 s[0:1], vcc
	s_cbranch_execz .LBB0_163
	v_pk_fma_f32 v[40:41], v[92:93], v[58:59], v[40:41] neg_lo:[1,0,0] neg_hi:[1,0,0]
	v_mov_b32_e32 v78, v58
	v_pk_fma_f32 v[40:41], v[40:41], v[60:61], v[88:89]
	v_mov_b32_e32 v79, v58
	v_max_f32_e32 v40, 0, v40
	v_max_f32_e32 v41, 0, v41
	v_pk_mul_f32 v[40:41], v[40:41], v[40:41]
	v_pk_fma_f32 v[46:47], v[102:103], v[78:79], v[46:47]
	v_mov_b32_e32 v80, v60
	v_mov_b32_e32 v81, v60
	v_pk_fma_f32 v[42:43], v[94:95], v[78:79], v[42:43]
	v_pk_fma_f32 v[42:43], v[42:43], v[80:81], v[90:91]
	v_max_f32_e32 v42, 0, v42
	v_max_f32_e32 v43, 0, v43
	v_pk_fma_f32 v[44:45], v[100:101], v[58:59], v[44:45] neg_lo:[1,0,0] neg_hi:[1,0,0]
	v_pk_mul_f32 v[42:43], v[42:43], v[42:43]
	v_pk_fma_f32 v[44:45], v[44:45], v[60:61], v[96:97]
	v_cvt_pk_bf16_f32 v40, v40, v41
	v_bfe_u32 v41, v43, 16, 1
	v_max_f32_e32 v44, 0, v44
	v_max_f32_e32 v45, 0, v45
	v_add3_u32 v41, v43, v41, s96
	v_bfe_u32 v43, v42, 16, 1
	v_pk_fma_f32 v[46:47], v[46:47], v[80:81], v[98:99]
	v_pk_mul_f32 v[44:45], v[44:45], v[44:45]
	v_add3_u32 v42, v42, v43, s96
	v_max_f32_e32 v46, 0, v46
	v_max_f32_e32 v47, 0, v47
	v_lshrrev_b32_e32 v42, 16, v42
	v_bfe_u32 v43, v44, 16, 1
	v_pk_mul_f32 v[46:47], v[46:47], v[46:47]
	v_and_or_b32 v41, v41, s97, v42
	v_bfe_u32 v42, v45, 16, 1
	v_add3_u32 v43, v44, v43, s96
	v_add3_u32 v42, v45, v42, s96
	v_lshrrev_b32_e32 v43, 16, v43
	v_and_or_b32 v42, v42, s97, v43
	v_cvt_pk_bf16_f32 v43, v46, v47
	global_store_dwordx4 v[62:63], v[40:43], off

.LBB0_165:
	s_or_b64 exec, exec, s[0:1]
	s_waitcnt vmcnt(2)
	v_pk_add_f32 v[32:33], v[52:53], v[54:55]
	v_pk_add_f32 v[34:35], v[48:49], v[50:51]
	s_mov_b32 s0, 0x3a800000
	v_pk_add_f32 v[32:33], v[32:33], v[34:35]
	v_add_u32_e32 v40, 0xb0, v198
	v_pk_mul_f32 v[42:43], v[32:33], s[0:1] op_sel_hi:[1,0]
	s_mov_b32 s0, 0x800000
	v_fma_f32 v32, -v42, v42, v43
	v_max_f32_e32 v32, 0, v32
	v_add_f32_e32 v32, 0x3727c5ac, v32
	v_cmp_gt_f32_e64 s[0:1], s0, v32
	v_mul_f32_e32 v33, 0x4b800000, v32
	v_ashrrev_i32_e32 v41, 31, v40
	v_cndmask_b32_e64 v32, v32, v33, s[0:1]
	v_rsq_f32_e32 v32, v32
	v_lshlrev_b64 v[46:47], 13, v[56:57]
	v_lshl_add_u64 v[46:47], s[24:25], 0, v[46:47]
	v_mul_f32_e32 v33, 0x45800000, v32
	v_cndmask_b32_e64 v44, v32, v33, s[0:1]
	v_lshlrev_b64 v[32:33], 5, v[40:41]
	v_lshl_add_u64 v[32:33], s[56:57], 0, v[32:33]
	global_load_dwordx4 v[36:39], v[32:33], off offset:16
	s_nop 0
	global_load_dwordx4 v[32:35], v[32:33], off
	v_lshl_add_u64 v[46:47], v[196:197], 1, v[46:47]
	v_mov_b32_e32 v43, v42
	v_mov_b32_e32 v45, v44
	s_and_saveexec_b64 s[0:1], vcc
	s_cbranch_execz .LBB0_167
	v_pk_fma_f32 v[24:25], v[92:93], v[42:43], v[24:25] neg_lo:[1,0,0] neg_hi:[1,0,0]
	v_mov_b32_e32 v48, v42
	v_pk_fma_f32 v[24:25], v[24:25], v[44:45], v[88:89]
	v_mov_b32_e32 v49, v42
	v_max_f32_e32 v24, 0, v24
	v_max_f32_e32 v25, 0, v25
	v_pk_mul_f32 v[24:25], v[24:25], v[24:25]
	v_pk_fma_f32 v[30:31], v[102:103], v[48:49], v[30:31]
	v_mov_b32_e32 v50, v44
	v_mov_b32_e32 v51, v44
	v_pk_fma_f32 v[26:27], v[94:95], v[48:49], v[26:27]
	v_pk_fma_f32 v[26:27], v[26:27], v[50:51], v[90:91]
	v_max_f32_e32 v26, 0, v26
	v_max_f32_e32 v27, 0, v27
	v_pk_fma_f32 v[28:29], v[100:101], v[42:43], v[28:29] neg_lo:[1,0,0] neg_hi:[1,0,0]
	v_pk_mul_f32 v[26:27], v[26:27], v[26:27]
	v_pk_fma_f32 v[28:29], v[28:29], v[44:45], v[96:97]
	v_cvt_pk_bf16_f32 v24, v24, v25
	v_bfe_u32 v25, v27, 16, 1
	v_max_f32_e32 v28, 0, v28
	v_max_f32_e32 v29, 0, v29
	v_add3_u32 v25, v27, v25, s96
	v_bfe_u32 v27, v26, 16, 1
	v_pk_fma_f32 v[30:31], v[30:31], v[50:51], v[98:99]
	v_pk_mul_f32 v[28:29], v[28:29], v[28:29]
	v_add3_u32 v26, v26, v27, s96
	v_max_f32_e32 v30, 0, v30
	v_max_f32_e32 v31, 0, v31
	v_lshrrev_b32_e32 v26, 16, v26
	v_bfe_u32 v27, v28, 16, 1
	v_pk_mul_f32 v[30:31], v[30:31], v[30:31]
	v_and_or_b32 v25, v25, s97, v26
	v_bfe_u32 v26, v29, 16, 1
	v_add3_u32 v27, v28, v27, s96
	v_add3_u32 v26, v29, v26, s96
	v_lshrrev_b32_e32 v27, 16, v27
	v_and_or_b32 v26, v26, s97, v27
	v_cvt_pk_bf16_f32 v27, v30, v31
	global_store_dwordx4 v[46:47], v[24:27], off

.LBB0_169:
	s_or_b64 exec, exec, s[0:1]
	s_waitcnt vmcnt(2)
	v_pk_add_f32 v[16:17], v[36:37], v[38:39]
	v_pk_add_f32 v[18:19], v[32:33], v[34:35]
	s_mov_b32 s0, 0x3a800000
	v_pk_add_f32 v[16:17], v[18:19], v[16:17]
	s_nop 0
	v_pk_mul_f32 v[18:19], v[16:17], s[0:1] op_sel_hi:[1,0]
	s_mov_b32 s0, 0x800000
	v_fma_f32 v16, -v18, v18, v19
	v_max_f32_e32 v16, 0, v16
	v_add_f32_e32 v16, 0x3727c5ac, v16
	v_mul_f32_e32 v17, 0x4b800000, v16
	v_cmp_gt_f32_e64 s[0:1], s0, v16
	v_mov_b32_e32 v19, v18
	s_nop 0
	v_cndmask_b32_e64 v16, v16, v17, s[0:1]
	v_rsq_f32_e32 v16, v16
	s_nop 0
	v_mul_f32_e32 v17, 0x45800000, v16
	v_cndmask_b32_e64 v20, v16, v17, s[0:1]
	v_lshlrev_b64 v[16:17], 13, v[40:41]
	v_lshl_add_u64 v[16:17], s[24:25], 0, v[16:17]
	v_lshl_add_u64 v[16:17], v[196:197], 1, v[16:17]
	v_mov_b32_e32 v21, v20
	s_and_saveexec_b64 s[0:1], vcc
	s_cbranch_execz .LBB0_171
	v_pk_fma_f32 v[8:9], v[92:93], v[18:19], v[8:9] neg_lo:[1,0,0] neg_hi:[1,0,0]
	v_mov_b32_e32 v22, v18
	v_pk_fma_f32 v[8:9], v[8:9], v[20:21], v[88:89]
	v_mov_b32_e32 v23, v18
	v_max_f32_e32 v8, 0, v8
	v_max_f32_e32 v9, 0, v9
	v_pk_mul_f32 v[8:9], v[8:9], v[8:9]
	v_pk_fma_f32 v[14:15], v[102:103], v[22:23], v[14:15]
	v_mov_b32_e32 v24, v20
	v_mov_b32_e32 v25, v20
	v_pk_fma_f32 v[10:11], v[94:95], v[22:23], v[10:11]
	v_pk_fma_f32 v[10:11], v[10:11], v[24:25], v[90:91]
	v_max_f32_e32 v10, 0, v10
	v_max_f32_e32 v11, 0, v11
	v_pk_fma_f32 v[12:13], v[100:101], v[18:19], v[12:13] neg_lo:[1,0,0] neg_hi:[1,0,0]
	v_pk_mul_f32 v[10:11], v[10:11], v[10:11]
	v_pk_fma_f32 v[12:13], v[12:13], v[20:21], v[96:97]
	v_cvt_pk_bf16_f32 v8, v8, v9
	v_bfe_u32 v9, v11, 16, 1
	v_max_f32_e32 v12, 0, v12
	v_max_f32_e32 v13, 0, v13
	v_add3_u32 v9, v11, v9, s96
	v_bfe_u32 v11, v10, 16, 1
	v_pk_fma_f32 v[14:15], v[14:15], v[24:25], v[98:99]
	v_pk_mul_f32 v[12:13], v[12:13], v[12:13]
	v_add3_u32 v10, v10, v11, s96
	v_max_f32_e32 v14, 0, v14
	v_max_f32_e32 v15, 0, v15
	v_lshrrev_b32_e32 v10, 16, v10
	v_bfe_u32 v11, v12, 16, 1
	v_pk_mul_f32 v[14:15], v[14:15], v[14:15]
	v_and_or_b32 v9, v9, s97, v10
	v_bfe_u32 v10, v13, 16, 1
	v_add3_u32 v11, v12, v11, s96
	v_add3_u32 v10, v13, v10, s96
	v_lshrrev_b32_e32 v11, 16, v11
	v_and_or_b32 v10, v10, s97, v11
	v_cvt_pk_bf16_f32 v11, v14, v15
	global_store_dwordx4 v[16:17], v[8:11], off
